# baseline (speedup 1.0000x reference)
.LBB0_115:
	v_ashrrev_i32_e32 v108, 2, v65
	v_bfi_b32 v95, -16, v108, v65
	v_lshrrev_b32_e32 v2, 1, v65
	v_ashrrev_i32_e32 v64, 4, v65
	v_mad_i64_i32 v[0:1], s[2:3], s0, v95, 0
	v_and_b32_e32 v66, 24, v2
	v_add_u32_e32 v34, s70, v64
	v_and_b32_e32 v101, 15, v65
	v_lshl_add_u64 v[0:1], v[0:1], 1, s[34:35]
	v_lshlrev_b32_e32 v128, 1, v66
	s_waitcnt vmcnt(0)
	v_mad_i64_i32 v[16:17], s[2:3], s4, v34, 0
	v_lshl_add_u64 v[12:13], v[0:1], 0, v[128:129]
	v_lshl_add_u64 v[16:17], v[16:17], 1, s[40:41]
	v_lshlrev_b32_e32 v128, 4, v101
	v_lshl_add_u64 v[20:21], v[16:17], 0, v[128:129]
	v_mad_i64_i32 v[16:17], s[2:3], s92, v108, 0
	v_and_b32_e32 v67, 3, v65
	v_lshl_add_u64 v[16:17], v[16:17], 1, s[62:63]
	s_ashr_i32 s71, s70, 31
	v_lshl_add_u64 v[16:17], s[70:71], 1, v[16:17]
	v_lshlrev_b32_e32 v32, 4, v67
	v_mov_b32_e32 v33, v129
	s_lshl_b32 s66, s4, 6
	global_load_dwordx4 v[0:3], v[12:13], off
	global_load_dwordx4 v[4:7], v[12:13], off offset:64
	global_load_dwordx4 v[8:11], v[12:13], off offset:128
	s_nop 0
	global_load_dwordx4 v[12:15], v[12:13], off offset:192
	v_lshl_add_u64 v[28:29], v[16:17], 0, v[32:33]
	global_load_dwordx4 v[16:19], v[20:21], off
	v_lshl_add_u64 v[20:21], v[20:21], 0, s[66:67]
	global_load_dwordx4 v[20:23], v[20:21], off
	s_nop 0
	global_load_dwordx4 v[24:27], v[28:29], off
	s_nop 0
	global_load_dwordx4 v[28:31], v[28:29], off offset:64
	v_and_b32_e32 v33, 63, v65
	v_lshlrev_b32_e32 v33, 2, v33
	v_mov_b32_e32 v126, -1
	s_andn2_b64 vcc, exec, s[60:61]
	v_xor_b32_e32 v97, 64, v33
	v_xor_b32_e32 v99, 0x80, v33
	s_cbranch_vccnz .LBB0_133
	s_lshl_b32 s0, s47, 5
	s_lshl_b32 s1, s1, 3
	s_add_i32 s0, s1, s0
	s_ashr_i32 s1, s0, 31
	s_lshl_b64 s[0:1], s[0:1], 9
	v_readlane_b32 s2, v254, 33
	s_add_u32 s0, s2, s0
	v_readlane_b32 s2, v254, 34
	s_addc_u32 s1, s2, s1
	v_lshlrev_b32_e32 v36, 2, v66
	v_mov_b32_e32 v37, v129
	s_cmpk_gt_u32 s45, 0xff
	v_lshl_add_u64 v[52:53], s[0:1], 0, v[36:37]
	v_xor_b32_e32 v69, 64, v33
	v_xor_b32_e32 v35, 0x80, v33
	v_mov_b32_e32 v76, 0xf149f2ca
	s_cselect_b64 s[94:95], -1, 0
	s_cmpk_lt_u32 s45, 0x100
	s_waitcnt vmcnt(6)
	v_lshlrev_b32_e32 v63, 16, v4
	v_lshlrev_b32_e32 v62, 16, v0
	v_and_b32_e32 v75, 0xffff0000, v4
	v_and_b32_e32 v74, 0xffff0000, v0
	v_lshlrev_b32_e32 v73, 16, v5
	v_lshlrev_b32_e32 v72, 16, v1
	v_and_b32_e32 v71, 0xffff0000, v5
	v_and_b32_e32 v70, 0xffff0000, v1
	v_lshlrev_b32_e32 v61, 16, v6
	v_lshlrev_b32_e32 v60, 16, v2
	v_and_b32_e32 v59, 0xffff0000, v6
	v_and_b32_e32 v58, 0xffff0000, v2
	v_lshlrev_b32_e32 v57, 16, v7
	v_lshlrev_b32_e32 v56, 16, v3
	v_and_b32_e32 v55, 0xffff0000, v7
	v_and_b32_e32 v54, 0xffff0000, v3
	s_waitcnt vmcnt(4)
	v_lshlrev_b32_e32 v49, 16, v12
	v_lshlrev_b32_e32 v48, 16, v8
	v_and_b32_e32 v51, 0xffff0000, v12
	v_and_b32_e32 v50, 0xffff0000, v8
	v_lshlrev_b32_e32 v47, 16, v13
	v_lshlrev_b32_e32 v46, 16, v9
	v_and_b32_e32 v45, 0xffff0000, v13
	v_and_b32_e32 v44, 0xffff0000, v9
	v_lshlrev_b32_e32 v43, 16, v14
	v_lshlrev_b32_e32 v42, 16, v10
	v_and_b32_e32 v41, 0xffff0000, v14
	v_and_b32_e32 v40, 0xffff0000, v10
	v_lshlrev_b32_e32 v39, 16, v15
	v_lshlrev_b32_e32 v38, 16, v11
	v_and_b32_e32 v37, 0xffff0000, v15
	v_and_b32_e32 v36, 0xffff0000, v11
	v_mov_b32_e32 v77, 0xf149f2ca
	s_cbranch_scc1 .LBB0_118
	global_load_dwordx4 v[78:81], v[52:53], off offset:16
	global_load_dwordx4 v[82:85], v[52:53], off
	global_load_dwordx4 v[86:89], v[52:53], off offset:144
	global_load_dwordx4 v[90:93], v[52:53], off offset:128
	global_load_dwordx4 v[170:173], v[52:53], off offset:272
	global_load_dwordx4 v[174:177], v[52:53], off offset:256
	global_load_dwordx4 v[178:181], v[52:53], off offset:400
	global_load_dwordx4 v[182:185], v[52:53], off offset:384
	s_waitcnt vmcnt(6)
	v_mov_b32_e32 v102, v82
	s_waitcnt vmcnt(4)
	v_mov_b32_e32 v103, v90
	v_mov_b32_e32 v90, v83
	v_pk_mul_f32 v[82:83], v[90:91], v[74:75]
	v_mov_b32_e32 v90, v84
	v_pk_fma_f32 v[82:83], v[102:103], v[62:63], v[82:83]
	v_mov_b32_e32 v91, v92
	v_pk_fma_f32 v[82:83], v[90:91], v[72:73], v[82:83]
	v_mov_b32_e32 v92, v85
	v_pk_fma_f32 v[82:83], v[92:93], v[70:71], v[82:83]
	v_mov_b32_e32 v84, v78
	v_mov_b32_e32 v85, v86
	v_pk_fma_f32 v[82:83], v[84:85], v[60:61], v[82:83]
	v_mov_b32_e32 v86, v79
	v_pk_fma_f32 v[78:79], v[86:87], v[58:59], v[82:83]
	v_mov_b32_e32 v82, v80
	v_mov_b32_e32 v83, v88
	v_pk_fma_f32 v[78:79], v[82:83], v[56:57], v[78:79]
	v_mov_b32_e32 v88, v81
	v_pk_fma_f32 v[78:79], v[88:89], v[54:55], v[78:79]
	s_nop 0
	v_add_f32_e32 v77, 0, v78
	v_add_f32_e32 v77, v77, v79
	s_waitcnt vmcnt(0)
	v_mov_b32_e32 v78, v170
	v_mov_b32_e32 v79, v171
	v_mov_b32_e32 v80, v172
	v_mov_b32_e32 v81, v173
	v_mov_b32_e32 v82, v174
	v_mov_b32_e32 v83, v175
	v_mov_b32_e32 v84, v176
	v_mov_b32_e32 v85, v177
	v_mov_b32_e32 v86, v178
	v_mov_b32_e32 v87, v179
	v_mov_b32_e32 v88, v180
	v_mov_b32_e32 v89, v181
	v_mov_b32_e32 v90, v182
	v_mov_b32_e32 v91, v183
	v_mov_b32_e32 v92, v184
	v_mov_b32_e32 v93, v185
	s_waitcnt vmcnt(2)
	v_mov_b32_e32 v102, v82
	s_waitcnt vmcnt(0)
	v_mov_b32_e32 v103, v90
	v_mov_b32_e32 v90, v83
	v_pk_mul_f32 v[82:83], v[90:91], v[50:51]
	v_mov_b32_e32 v90, v84
	v_pk_fma_f32 v[82:83], v[102:103], v[48:49], v[82:83]
	v_mov_b32_e32 v91, v92
	v_pk_fma_f32 v[82:83], v[90:91], v[46:47], v[82:83]
	v_mov_b32_e32 v92, v85
	v_pk_fma_f32 v[82:83], v[92:93], v[44:45], v[82:83]
	v_mov_b32_e32 v84, v78
	v_mov_b32_e32 v85, v86
	v_pk_fma_f32 v[82:83], v[84:85], v[42:43], v[82:83]
	v_mov_b32_e32 v86, v79
	v_pk_fma_f32 v[78:79], v[86:87], v[40:41], v[82:83]
	v_mov_b32_e32 v82, v80
	v_mov_b32_e32 v83, v88
	v_pk_fma_f32 v[78:79], v[82:83], v[38:39], v[78:79]
	v_mov_b32_e32 v88, v81
	v_pk_fma_f32 v[78:79], v[88:89], v[36:37], v[78:79]
	s_nop 0
	v_add_f32_e32 v77, v77, v78
	v_add_f32_e32 v77, v77, v79
	ds_bpermute_b32 v78, v69, v77
	s_waitcnt lgkmcnt(0)
	v_add_f32_e32 v77, v77, v78
	ds_bpermute_b32 v78, v35, v77
	s_waitcnt lgkmcnt(0)
	v_add_f32_e32 v77, v77, v78
.LBB0_118:
	s_cmpk_gt_u32 s45, 0x1ff
	s_cselect_b64 s[96:97], -1, 0
	s_cmpk_lt_u32 s45, 0x200
	s_cbranch_scc1 .LBB0_120
	global_load_dwordx4 v[78:81], v[52:53], off offset:528
	global_load_dwordx4 v[82:85], v[52:53], off offset:512
	global_load_dwordx4 v[86:89], v[52:53], off offset:656
	global_load_dwordx4 v[90:93], v[52:53], off offset:640
	global_load_dwordx4 v[170:173], v[52:53], off offset:784
	global_load_dwordx4 v[174:177], v[52:53], off offset:768
	global_load_dwordx4 v[178:181], v[52:53], off offset:912
	global_load_dwordx4 v[182:185], v[52:53], off offset:896
	s_waitcnt vmcnt(6)
	v_mov_b32_e32 v102, v82
	s_waitcnt vmcnt(4)
	v_mov_b32_e32 v103, v90
	v_mov_b32_e32 v90, v83
	v_pk_mul_f32 v[82:83], v[90:91], v[74:75]
	v_mov_b32_e32 v90, v84
	v_pk_fma_f32 v[82:83], v[102:103], v[62:63], v[82:83]
	v_mov_b32_e32 v91, v92
	v_pk_fma_f32 v[82:83], v[90:91], v[72:73], v[82:83]
	v_mov_b32_e32 v92, v85
	v_pk_fma_f32 v[82:83], v[92:93], v[70:71], v[82:83]
	v_mov_b32_e32 v84, v78
	v_mov_b32_e32 v85, v86
	v_pk_fma_f32 v[82:83], v[84:85], v[60:61], v[82:83]
	v_mov_b32_e32 v86, v79
	v_pk_fma_f32 v[78:79], v[86:87], v[58:59], v[82:83]
	v_mov_b32_e32 v82, v80
	v_mov_b32_e32 v83, v88
	v_pk_fma_f32 v[78:79], v[82:83], v[56:57], v[78:79]
	v_mov_b32_e32 v88, v81
	v_pk_fma_f32 v[78:79], v[88:89], v[54:55], v[78:79]
	s_nop 0
	v_add_f32_e32 v76, 0, v78
	v_add_f32_e32 v76, v76, v79
	s_waitcnt vmcnt(0)
	v_mov_b32_e32 v78, v170
	v_mov_b32_e32 v79, v171
	v_mov_b32_e32 v80, v172
	v_mov_b32_e32 v81, v173
	v_mov_b32_e32 v82, v174
	v_mov_b32_e32 v83, v175
	v_mov_b32_e32 v84, v176
	v_mov_b32_e32 v85, v177
	v_mov_b32_e32 v86, v178
	v_mov_b32_e32 v87, v179
	v_mov_b32_e32 v88, v180
	v_mov_b32_e32 v89, v181
	v_mov_b32_e32 v90, v182
	v_mov_b32_e32 v91, v183
	v_mov_b32_e32 v92, v184
	v_mov_b32_e32 v93, v185
	s_waitcnt vmcnt(2)
	v_mov_b32_e32 v102, v82
	s_waitcnt vmcnt(0)
	v_mov_b32_e32 v103, v90
	v_mov_b32_e32 v90, v83
	v_pk_mul_f32 v[82:83], v[90:91], v[50:51]
	v_mov_b32_e32 v90, v84
	v_pk_fma_f32 v[82:83], v[102:103], v[48:49], v[82:83]
	v_mov_b32_e32 v91, v92
	v_pk_fma_f32 v[82:83], v[90:91], v[46:47], v[82:83]
	v_mov_b32_e32 v92, v85
	v_pk_fma_f32 v[82:83], v[92:93], v[44:45], v[82:83]
	v_mov_b32_e32 v84, v78
	v_mov_b32_e32 v85, v86
	v_pk_fma_f32 v[82:83], v[84:85], v[42:43], v[82:83]
	v_mov_b32_e32 v86, v79
	v_pk_fma_f32 v[78:79], v[86:87], v[40:41], v[82:83]
	v_mov_b32_e32 v82, v80
	v_mov_b32_e32 v83, v88
	v_pk_fma_f32 v[78:79], v[82:83], v[38:39], v[78:79]
	v_mov_b32_e32 v88, v81
	v_pk_fma_f32 v[78:79], v[88:89], v[36:37], v[78:79]
	s_nop 0
	v_add_f32_e32 v76, v76, v78
	v_add_f32_e32 v76, v76, v79
	ds_bpermute_b32 v78, v69, v76
	s_waitcnt lgkmcnt(0)
	v_add_f32_e32 v76, v76, v78
	ds_bpermute_b32 v78, v35, v76
	s_waitcnt lgkmcnt(0)
	v_add_f32_e32 v76, v76, v78
.LBB0_120:
	s_cmpk_gt_u32 s45, 0x2ff
	v_mov_b32_e32 v78, 0xf149f2ca
	s_cselect_b64 s[0:1], -1, 0
	s_cmpk_lt_u32 s45, 0x300
	v_mov_b32_e32 v79, 0xf149f2ca
	s_cbranch_scc1 .LBB0_122
	global_load_dwordx4 v[80:83], v[52:53], off offset:1040
	global_load_dwordx4 v[84:87], v[52:53], off offset:1024
	global_load_dwordx4 v[88:91], v[52:53], off offset:1168
	global_load_dwordx4 v[102:105], v[52:53], off offset:1152
	global_load_dwordx4 v[170:173], v[52:53], off offset:1296
	global_load_dwordx4 v[174:177], v[52:53], off offset:1280
	global_load_dwordx4 v[178:181], v[52:53], off offset:1424
	global_load_dwordx4 v[182:185], v[52:53], off offset:1408
	s_waitcnt vmcnt(6)
	v_mov_b32_e32 v92, v84
	s_waitcnt vmcnt(4)
	v_mov_b32_e32 v93, v102
	v_mov_b32_e32 v102, v85
	v_pk_mul_f32 v[84:85], v[102:103], v[74:75]
	s_nop 0
	v_pk_fma_f32 v[84:85], v[92:93], v[62:63], v[84:85]
	v_mov_b32_e32 v92, v86
	v_mov_b32_e32 v93, v104
	v_pk_fma_f32 v[84:85], v[92:93], v[72:73], v[84:85]
	v_mov_b32_e32 v104, v87
	v_pk_fma_f32 v[84:85], v[104:105], v[70:71], v[84:85]
	v_mov_b32_e32 v86, v80
	v_mov_b32_e32 v87, v88
	v_pk_fma_f32 v[84:85], v[86:87], v[60:61], v[84:85]
	v_mov_b32_e32 v88, v81
	v_pk_fma_f32 v[80:81], v[88:89], v[58:59], v[84:85]
	v_mov_b32_e32 v84, v82
	v_mov_b32_e32 v85, v90
	v_pk_fma_f32 v[80:81], v[84:85], v[56:57], v[80:81]
	v_mov_b32_e32 v90, v83
	v_pk_fma_f32 v[80:81], v[90:91], v[54:55], v[80:81]
	s_nop 0
	v_add_f32_e32 v79, 0, v80
	v_add_f32_e32 v79, v79, v81
	s_waitcnt vmcnt(0)
	v_mov_b32_e32 v80, v170
	v_mov_b32_e32 v81, v171
	v_mov_b32_e32 v82, v172
	v_mov_b32_e32 v83, v173
	v_mov_b32_e32 v84, v174
	v_mov_b32_e32 v85, v175
	v_mov_b32_e32 v86, v176
	v_mov_b32_e32 v87, v177
	v_mov_b32_e32 v88, v178
	v_mov_b32_e32 v89, v179
	v_mov_b32_e32 v90, v180
	v_mov_b32_e32 v91, v181
	v_mov_b32_e32 v102, v182
	v_mov_b32_e32 v103, v183
	v_mov_b32_e32 v104, v184
	v_mov_b32_e32 v105, v185
	s_waitcnt vmcnt(2)
	v_mov_b32_e32 v92, v84
	s_waitcnt vmcnt(0)
	v_mov_b32_e32 v93, v102
	v_mov_b32_e32 v102, v85
	v_pk_mul_f32 v[84:85], v[102:103], v[50:51]
	s_nop 0
	v_pk_fma_f32 v[84:85], v[92:93], v[48:49], v[84:85]
	v_mov_b32_e32 v92, v86
	v_mov_b32_e32 v93, v104
	v_pk_fma_f32 v[84:85], v[92:93], v[46:47], v[84:85]
	v_mov_b32_e32 v104, v87
	v_pk_fma_f32 v[84:85], v[104:105], v[44:45], v[84:85]
	v_mov_b32_e32 v86, v80
	v_mov_b32_e32 v87, v88
	v_pk_fma_f32 v[84:85], v[86:87], v[42:43], v[84:85]
	v_mov_b32_e32 v88, v81
	v_pk_fma_f32 v[80:81], v[88:89], v[40:41], v[84:85]
	v_mov_b32_e32 v84, v82
	v_mov_b32_e32 v85, v90
	v_pk_fma_f32 v[80:81], v[84:85], v[38:39], v[80:81]
	v_mov_b32_e32 v90, v83
	v_pk_fma_f32 v[80:81], v[90:91], v[36:37], v[80:81]
	s_nop 0
	v_add_f32_e32 v79, v79, v80
	v_add_f32_e32 v79, v79, v81
	ds_bpermute_b32 v80, v69, v79
	s_waitcnt lgkmcnt(0)
	v_add_f32_e32 v79, v79, v80
	ds_bpermute_b32 v80, v35, v79
	s_waitcnt lgkmcnt(0)
	v_add_f32_e32 v79, v79, v80
.LBB0_122:
	s_cmpk_gt_u32 s45, 0x3ff
	s_cselect_b64 s[98:99], -1, 0
	s_cmpk_lt_u32 s45, 0x400
	s_cbranch_scc1 .LBB0_124
	global_load_dwordx4 v[80:83], v[52:53], off offset:1552
	global_load_dwordx4 v[84:87], v[52:53], off offset:1536
	global_load_dwordx4 v[88:91], v[52:53], off offset:1680
	global_load_dwordx4 v[102:105], v[52:53], off offset:1664
	global_load_dwordx4 v[170:173], v[52:53], off offset:1808
	global_load_dwordx4 v[174:177], v[52:53], off offset:1792
	global_load_dwordx4 v[178:181], v[52:53], off offset:1936
	global_load_dwordx4 v[182:185], v[52:53], off offset:1920
	s_waitcnt vmcnt(6)
	v_mov_b32_e32 v92, v84
	s_waitcnt vmcnt(4)
	v_mov_b32_e32 v93, v102
	v_mov_b32_e32 v102, v85
	v_pk_mul_f32 v[84:85], v[102:103], v[74:75]
	s_nop 0
	v_pk_fma_f32 v[84:85], v[92:93], v[62:63], v[84:85]
	v_mov_b32_e32 v92, v86
	v_mov_b32_e32 v93, v104
	v_pk_fma_f32 v[84:85], v[92:93], v[72:73], v[84:85]
	v_mov_b32_e32 v104, v87
	v_pk_fma_f32 v[84:85], v[104:105], v[70:71], v[84:85]
	v_mov_b32_e32 v86, v80
	v_mov_b32_e32 v87, v88
	v_pk_fma_f32 v[84:85], v[86:87], v[60:61], v[84:85]
	v_mov_b32_e32 v88, v81
	v_pk_fma_f32 v[80:81], v[88:89], v[58:59], v[84:85]
	v_mov_b32_e32 v84, v82
	v_mov_b32_e32 v85, v90
	v_pk_fma_f32 v[80:81], v[84:85], v[56:57], v[80:81]
	v_mov_b32_e32 v90, v83
	v_pk_fma_f32 v[80:81], v[90:91], v[54:55], v[80:81]
	s_nop 0
	v_add_f32_e32 v78, 0, v80
	v_add_f32_e32 v78, v78, v81
	s_waitcnt vmcnt(0)
	v_mov_b32_e32 v80, v170
	v_mov_b32_e32 v81, v171
	v_mov_b32_e32 v82, v172
	v_mov_b32_e32 v83, v173
	v_mov_b32_e32 v84, v174
	v_mov_b32_e32 v85, v175
	v_mov_b32_e32 v86, v176
	v_mov_b32_e32 v87, v177
	v_mov_b32_e32 v88, v178
	v_mov_b32_e32 v89, v179
	v_mov_b32_e32 v90, v180
	v_mov_b32_e32 v91, v181
	v_mov_b32_e32 v102, v182
	v_mov_b32_e32 v103, v183
	v_mov_b32_e32 v104, v184
	v_mov_b32_e32 v105, v185
	s_waitcnt vmcnt(2)
	v_mov_b32_e32 v92, v84
	s_waitcnt vmcnt(0)
	v_mov_b32_e32 v93, v102
	v_mov_b32_e32 v102, v85
	v_pk_mul_f32 v[84:85], v[102:103], v[50:51]
	s_nop 0
	v_pk_fma_f32 v[84:85], v[92:93], v[48:49], v[84:85]
	v_mov_b32_e32 v92, v86
	v_mov_b32_e32 v93, v104
	v_pk_fma_f32 v[84:85], v[92:93], v[46:47], v[84:85]
	v_mov_b32_e32 v104, v87
	v_pk_fma_f32 v[84:85], v[104:105], v[44:45], v[84:85]
	v_mov_b32_e32 v86, v80
	v_mov_b32_e32 v87, v88
	v_pk_fma_f32 v[84:85], v[86:87], v[42:43], v[84:85]
	v_mov_b32_e32 v88, v81
	v_pk_fma_f32 v[80:81], v[88:89], v[40:41], v[84:85]
	v_mov_b32_e32 v84, v82
	v_mov_b32_e32 v85, v90
	v_pk_fma_f32 v[80:81], v[84:85], v[38:39], v[80:81]
	v_mov_b32_e32 v90, v83
	v_pk_fma_f32 v[80:81], v[90:91], v[36:37], v[80:81]
	s_nop 0
	v_add_f32_e32 v78, v78, v80
	v_add_f32_e32 v78, v78, v81
	ds_bpermute_b32 v80, v69, v78
	s_waitcnt lgkmcnt(0)
	v_add_f32_e32 v78, v78, v80
	ds_bpermute_b32 v80, v35, v78
	s_waitcnt lgkmcnt(0)
	v_add_f32_e32 v78, v78, v80
.LBB0_124:
	s_cmpk_gt_u32 s45, 0x4ff
	v_mov_b32_e32 v80, 0xf149f2ca
	s_cselect_b64 s[54:55], -1, 0
	s_cmpk_lt_u32 s45, 0x500
	v_mov_b32_e32 v81, 0xf149f2ca
	s_cbranch_scc1 .LBB0_126
	global_load_dwordx4 v[82:85], v[52:53], off offset:2064
	global_load_dwordx4 v[86:89], v[52:53], off offset:2048
	global_load_dwordx4 v[90:93], v[52:53], off offset:2192
	global_load_dwordx4 v[102:105], v[52:53], off offset:2176
	global_load_dwordx4 v[170:173], v[52:53], off offset:2320
	global_load_dwordx4 v[174:177], v[52:53], off offset:2304
	global_load_dwordx4 v[178:181], v[52:53], off offset:2448
	global_load_dwordx4 v[182:185], v[52:53], off offset:2432
	s_waitcnt vmcnt(6)
	v_mov_b32_e32 v106, v86
	s_waitcnt vmcnt(4)
	v_mov_b32_e32 v107, v102
	v_mov_b32_e32 v102, v87
	v_pk_mul_f32 v[86:87], v[102:103], v[74:75]
	v_mov_b32_e32 v102, v88
	v_pk_fma_f32 v[86:87], v[106:107], v[62:63], v[86:87]
	v_mov_b32_e32 v103, v104
	v_pk_fma_f32 v[86:87], v[102:103], v[72:73], v[86:87]
	v_mov_b32_e32 v104, v89
	v_pk_fma_f32 v[86:87], v[104:105], v[70:71], v[86:87]
	v_mov_b32_e32 v88, v82
	v_mov_b32_e32 v89, v90
	v_pk_fma_f32 v[86:87], v[88:89], v[60:61], v[86:87]
	v_mov_b32_e32 v90, v83
	v_pk_fma_f32 v[82:83], v[90:91], v[58:59], v[86:87]
	v_mov_b32_e32 v86, v84
	v_mov_b32_e32 v87, v92
	v_pk_fma_f32 v[82:83], v[86:87], v[56:57], v[82:83]
	v_mov_b32_e32 v92, v85
	v_pk_fma_f32 v[82:83], v[92:93], v[54:55], v[82:83]
	s_nop 0
	v_add_f32_e32 v81, 0, v82
	v_add_f32_e32 v81, v81, v83
	s_waitcnt vmcnt(0)
	v_mov_b32_e32 v82, v170
	v_mov_b32_e32 v83, v171
	v_mov_b32_e32 v84, v172
	v_mov_b32_e32 v85, v173
	v_mov_b32_e32 v86, v174
	v_mov_b32_e32 v87, v175
	v_mov_b32_e32 v88, v176
	v_mov_b32_e32 v89, v177
	v_mov_b32_e32 v90, v178
	v_mov_b32_e32 v91, v179
	v_mov_b32_e32 v92, v180
	v_mov_b32_e32 v93, v181
	v_mov_b32_e32 v102, v182
	v_mov_b32_e32 v103, v183
	v_mov_b32_e32 v104, v184
	v_mov_b32_e32 v105, v185
	s_waitcnt vmcnt(2)
	v_mov_b32_e32 v106, v86
	s_waitcnt vmcnt(0)
	v_mov_b32_e32 v107, v102
	v_mov_b32_e32 v102, v87
	v_pk_mul_f32 v[86:87], v[102:103], v[50:51]
	v_mov_b32_e32 v102, v88
	v_pk_fma_f32 v[86:87], v[106:107], v[48:49], v[86:87]
	v_mov_b32_e32 v103, v104
	v_pk_fma_f32 v[86:87], v[102:103], v[46:47], v[86:87]
	v_mov_b32_e32 v104, v89
	v_pk_fma_f32 v[86:87], v[104:105], v[44:45], v[86:87]
	v_mov_b32_e32 v88, v82
	v_mov_b32_e32 v89, v90
	v_pk_fma_f32 v[86:87], v[88:89], v[42:43], v[86:87]
	v_mov_b32_e32 v90, v83
	v_pk_fma_f32 v[82:83], v[90:91], v[40:41], v[86:87]
	v_mov_b32_e32 v86, v84
	v_mov_b32_e32 v87, v92
	v_pk_fma_f32 v[82:83], v[86:87], v[38:39], v[82:83]
	v_mov_b32_e32 v92, v85
	v_pk_fma_f32 v[82:83], v[92:93], v[36:37], v[82:83]
	s_nop 0
	v_add_f32_e32 v81, v81, v82
	v_add_f32_e32 v81, v81, v83
	ds_bpermute_b32 v82, v69, v81
	s_waitcnt lgkmcnt(0)
	v_add_f32_e32 v81, v81, v82
	ds_bpermute_b32 v82, v35, v81
	s_waitcnt lgkmcnt(0)
	v_add_f32_e32 v81, v81, v82
.LBB0_126:
	s_cmpk_gt_u32 s45, 0x5ff
	s_cselect_b64 s[42:43], -1, 0
	s_cmpk_lt_u32 s45, 0x600
	s_cbranch_scc1 .LBB0_128
	global_load_dwordx4 v[82:85], v[52:53], off offset:2576
	global_load_dwordx4 v[86:89], v[52:53], off offset:2560
	global_load_dwordx4 v[90:93], v[52:53], off offset:2704
	global_load_dwordx4 v[102:105], v[52:53], off offset:2688
	global_load_dwordx4 v[170:173], v[52:53], off offset:2832
	global_load_dwordx4 v[174:177], v[52:53], off offset:2816
	global_load_dwordx4 v[178:181], v[52:53], off offset:2960
	global_load_dwordx4 v[182:185], v[52:53], off offset:2944
	s_waitcnt vmcnt(6)
	v_mov_b32_e32 v106, v86
	s_waitcnt vmcnt(4)
	v_mov_b32_e32 v107, v102
	v_mov_b32_e32 v102, v87
	v_pk_mul_f32 v[86:87], v[102:103], v[74:75]
	v_mov_b32_e32 v102, v88
	v_pk_fma_f32 v[86:87], v[106:107], v[62:63], v[86:87]
	v_mov_b32_e32 v103, v104
	v_pk_fma_f32 v[86:87], v[102:103], v[72:73], v[86:87]
	v_mov_b32_e32 v104, v89
	v_pk_fma_f32 v[86:87], v[104:105], v[70:71], v[86:87]
	v_mov_b32_e32 v88, v82
	v_mov_b32_e32 v89, v90
	v_pk_fma_f32 v[86:87], v[88:89], v[60:61], v[86:87]
	v_mov_b32_e32 v90, v83
	v_pk_fma_f32 v[82:83], v[90:91], v[58:59], v[86:87]
	v_mov_b32_e32 v86, v84
	v_mov_b32_e32 v87, v92
	v_pk_fma_f32 v[82:83], v[86:87], v[56:57], v[82:83]
	v_mov_b32_e32 v92, v85
	v_pk_fma_f32 v[82:83], v[92:93], v[54:55], v[82:83]
	s_nop 0
	v_add_f32_e32 v80, 0, v82
	v_add_f32_e32 v80, v80, v83
	s_waitcnt vmcnt(0)
	v_mov_b32_e32 v82, v170
	v_mov_b32_e32 v83, v171
	v_mov_b32_e32 v84, v172
	v_mov_b32_e32 v85, v173
	v_mov_b32_e32 v86, v174
	v_mov_b32_e32 v87, v175
	v_mov_b32_e32 v88, v176
	v_mov_b32_e32 v89, v177
	v_mov_b32_e32 v90, v178
	v_mov_b32_e32 v91, v179
	v_mov_b32_e32 v92, v180
	v_mov_b32_e32 v93, v181
	v_mov_b32_e32 v102, v182
	v_mov_b32_e32 v103, v183
	v_mov_b32_e32 v104, v184
	v_mov_b32_e32 v105, v185
	s_waitcnt vmcnt(2)
	v_mov_b32_e32 v106, v86
	s_waitcnt vmcnt(0)
	v_mov_b32_e32 v107, v102
	v_mov_b32_e32 v102, v87
	v_pk_mul_f32 v[86:87], v[102:103], v[50:51]
	v_mov_b32_e32 v102, v88
	v_pk_fma_f32 v[86:87], v[106:107], v[48:49], v[86:87]
	v_mov_b32_e32 v103, v104
	v_pk_fma_f32 v[86:87], v[102:103], v[46:47], v[86:87]
	v_mov_b32_e32 v104, v89
	v_pk_fma_f32 v[86:87], v[104:105], v[44:45], v[86:87]
	v_mov_b32_e32 v88, v82
	v_mov_b32_e32 v89, v90
	v_pk_fma_f32 v[86:87], v[88:89], v[42:43], v[86:87]
	v_mov_b32_e32 v90, v83
	v_pk_fma_f32 v[82:83], v[90:91], v[40:41], v[86:87]
	v_mov_b32_e32 v86, v84
	v_mov_b32_e32 v87, v92
	v_pk_fma_f32 v[82:83], v[86:87], v[38:39], v[82:83]
	v_mov_b32_e32 v92, v85
	v_pk_fma_f32 v[82:83], v[92:93], v[36:37], v[82:83]
	s_nop 0
	v_add_f32_e32 v80, v80, v82
	v_add_f32_e32 v80, v80, v83
	ds_bpermute_b32 v82, v69, v80
	s_waitcnt lgkmcnt(0)
	v_add_f32_e32 v80, v80, v82
	ds_bpermute_b32 v82, v35, v80
	s_waitcnt lgkmcnt(0)
	v_add_f32_e32 v80, v80, v82
.LBB0_128:
	s_cmpk_gt_u32 s45, 0x6ff
	v_mov_b32_e32 v82, 0xf149f2ca
	s_cselect_b64 s[34:35], -1, 0
	s_cmpk_lt_u32 s45, 0x700
	v_mov_b32_e32 v83, 0xf149f2ca
	s_cbranch_scc1 .LBB0_130
	global_load_dwordx4 v[84:87], v[52:53], off offset:3088
	global_load_dwordx4 v[88:91], v[52:53], off offset:3072
	global_load_dwordx4 v[102:105], v[52:53], off offset:3216
	global_load_dwordx4 v[110:113], v[52:53], off offset:3200
	global_load_dwordx4 v[170:173], v[52:53], off offset:3344
	global_load_dwordx4 v[174:177], v[52:53], off offset:3328
	global_load_dwordx4 v[178:181], v[52:53], off offset:3472
	global_load_dwordx4 v[182:185], v[52:53], off offset:3456
	s_waitcnt vmcnt(6)
	v_mov_b32_e32 v92, v88
	s_waitcnt vmcnt(4)
	v_mov_b32_e32 v93, v110
	v_mov_b32_e32 v110, v89
	v_pk_mul_f32 v[88:89], v[110:111], v[74:75]
	s_nop 0
	v_pk_fma_f32 v[88:89], v[92:93], v[62:63], v[88:89]
	v_mov_b32_e32 v92, v90
	v_mov_b32_e32 v93, v112
	v_pk_fma_f32 v[88:89], v[92:93], v[72:73], v[88:89]
	v_mov_b32_e32 v112, v91
	v_pk_fma_f32 v[88:89], v[112:113], v[70:71], v[88:89]
	v_mov_b32_e32 v90, v84
	v_mov_b32_e32 v91, v102
	v_pk_fma_f32 v[88:89], v[90:91], v[60:61], v[88:89]
	v_mov_b32_e32 v102, v85
	v_pk_fma_f32 v[84:85], v[102:103], v[58:59], v[88:89]
	v_mov_b32_e32 v88, v86
	v_mov_b32_e32 v89, v104
	v_pk_fma_f32 v[84:85], v[88:89], v[56:57], v[84:85]
	v_mov_b32_e32 v104, v87
	v_pk_fma_f32 v[84:85], v[104:105], v[54:55], v[84:85]
	s_nop 0
	v_add_f32_e32 v83, 0, v84
	v_add_f32_e32 v83, v83, v85
	s_waitcnt vmcnt(0)
	v_mov_b32_e32 v84, v170
	v_mov_b32_e32 v85, v171
	v_mov_b32_e32 v86, v172
	v_mov_b32_e32 v87, v173
	v_mov_b32_e32 v88, v174
	v_mov_b32_e32 v89, v175
	v_mov_b32_e32 v90, v176
	v_mov_b32_e32 v91, v177
	v_mov_b32_e32 v102, v178
	v_mov_b32_e32 v103, v179
	v_mov_b32_e32 v104, v180
	v_mov_b32_e32 v105, v181
	v_mov_b32_e32 v110, v182
	v_mov_b32_e32 v111, v183
	v_mov_b32_e32 v112, v184
	v_mov_b32_e32 v113, v185
	s_waitcnt vmcnt(2)
	v_mov_b32_e32 v92, v88
	s_waitcnt vmcnt(0)
	v_mov_b32_e32 v93, v110
	v_mov_b32_e32 v110, v89
	v_pk_mul_f32 v[88:89], v[110:111], v[50:51]
	s_nop 0
	v_pk_fma_f32 v[88:89], v[92:93], v[48:49], v[88:89]
	v_mov_b32_e32 v92, v90
	v_mov_b32_e32 v93, v112
	v_pk_fma_f32 v[88:89], v[92:93], v[46:47], v[88:89]
	v_mov_b32_e32 v112, v91
	v_pk_fma_f32 v[88:89], v[112:113], v[44:45], v[88:89]
	v_mov_b32_e32 v90, v84
	v_mov_b32_e32 v91, v102
	v_pk_fma_f32 v[88:89], v[90:91], v[42:43], v[88:89]
	v_mov_b32_e32 v102, v85
	v_pk_fma_f32 v[84:85], v[102:103], v[40:41], v[88:89]
	v_mov_b32_e32 v88, v86
	v_mov_b32_e32 v89, v104
	v_pk_fma_f32 v[84:85], v[88:89], v[38:39], v[84:85]
	v_mov_b32_e32 v104, v87
	v_pk_fma_f32 v[84:85], v[104:105], v[36:37], v[84:85]
	s_nop 0
	v_add_f32_e32 v83, v83, v84
	v_add_f32_e32 v83, v83, v85
	ds_bpermute_b32 v84, v69, v83
	s_waitcnt lgkmcnt(0)
	v_add_f32_e32 v83, v83, v84
	ds_bpermute_b32 v84, v35, v83
	s_waitcnt lgkmcnt(0)
	v_add_f32_e32 v83, v83, v84
.LBB0_130:
	s_cmpk_gt_u32 s45, 0x7ff
	s_cselect_b64 s[88:89], -1, 0
	s_cmpk_lt_u32 s45, 0x800
	s_cbranch_scc1 .LBB0_132
	global_load_dwordx4 v[84:87], v[52:53], off offset:3600
	global_load_dwordx4 v[88:91], v[52:53], off offset:3584
	global_load_dwordx4 v[102:105], v[52:53], off offset:3728
	global_load_dwordx4 v[110:113], v[52:53], off offset:3712
	global_load_dwordx4 v[170:173], v[52:53], off offset:3856
	global_load_dwordx4 v[174:177], v[52:53], off offset:3840
	global_load_dwordx4 v[178:181], v[52:53], off offset:3984
	global_load_dwordx4 v[182:185], v[52:53], off offset:3968
	s_waitcnt vmcnt(6)
	v_mov_b32_e32 v92, v88
	s_waitcnt vmcnt(4)
	v_mov_b32_e32 v93, v110
	v_mov_b32_e32 v110, v89
	v_pk_mul_f32 v[74:75], v[110:111], v[74:75]
	s_nop 0
	v_pk_fma_f32 v[62:63], v[92:93], v[62:63], v[74:75]
	v_mov_b32_e32 v74, v90
	v_mov_b32_e32 v75, v112
	v_pk_fma_f32 v[62:63], v[74:75], v[72:73], v[62:63]
	v_mov_b32_e32 v112, v91
	v_pk_fma_f32 v[62:63], v[112:113], v[70:71], v[62:63]
	v_mov_b32_e32 v70, v84
	v_mov_b32_e32 v71, v102
	v_pk_fma_f32 v[60:61], v[70:71], v[60:61], v[62:63]
	v_mov_b32_e32 v102, v85
	v_pk_fma_f32 v[58:59], v[102:103], v[58:59], v[60:61]
	v_mov_b32_e32 v60, v86
	v_mov_b32_e32 v61, v104
	v_pk_fma_f32 v[56:57], v[60:61], v[56:57], v[58:59]
	v_mov_b32_e32 v104, v87
	v_pk_fma_f32 v[54:55], v[104:105], v[54:55], v[56:57]
	s_nop 0
	v_add_f32_e32 v54, 0, v54
	v_add_f32_e32 v62, v54, v55
	s_waitcnt vmcnt(0)
	v_mov_b32_e32 v54, v170
	v_mov_b32_e32 v55, v171
	v_mov_b32_e32 v56, v172
	v_mov_b32_e32 v57, v173
	v_mov_b32_e32 v58, v174
	v_mov_b32_e32 v59, v175
	v_mov_b32_e32 v60, v176
	v_mov_b32_e32 v61, v177
	v_mov_b32_e32 v70, v178
	v_mov_b32_e32 v71, v179
	v_mov_b32_e32 v72, v180
	v_mov_b32_e32 v73, v181
	v_mov_b32_e32 v84, v182
	v_mov_b32_e32 v85, v183
	v_mov_b32_e32 v86, v184
	v_mov_b32_e32 v87, v185
	s_waitcnt vmcnt(2)
	v_mov_b32_e32 v52, v58
	s_waitcnt vmcnt(0)
	v_mov_b32_e32 v53, v84
	v_mov_b32_e32 v84, v59
	v_pk_mul_f32 v[50:51], v[84:85], v[50:51]
	s_nop 0
	v_pk_fma_f32 v[48:49], v[52:53], v[48:49], v[50:51]
	v_mov_b32_e32 v50, v60
	v_mov_b32_e32 v51, v86
	v_pk_fma_f32 v[46:47], v[50:51], v[46:47], v[48:49]
	v_mov_b32_e32 v86, v61
	v_pk_fma_f32 v[44:45], v[86:87], v[44:45], v[46:47]
	v_mov_b32_e32 v46, v54
	v_mov_b32_e32 v47, v70
	v_pk_fma_f32 v[42:43], v[46:47], v[42:43], v[44:45]
	v_mov_b32_e32 v70, v55
	v_pk_fma_f32 v[40:41], v[70:71], v[40:41], v[42:43]
	v_mov_b32_e32 v42, v56
	v_mov_b32_e32 v43, v72
	v_pk_fma_f32 v[38:39], v[42:43], v[38:39], v[40:41]
	v_mov_b32_e32 v72, v57
	v_pk_fma_f32 v[36:37], v[72:73], v[36:37], v[38:39]
	s_nop 0
	v_add_f32_e32 v36, v62, v36
	v_add_f32_e32 v36, v36, v37
	ds_bpermute_b32 v37, v69, v36
	s_waitcnt lgkmcnt(0)
	v_add_f32_e32 v36, v36, v37
	ds_bpermute_b32 v35, v35, v36
	s_waitcnt lgkmcnt(0)
	v_add_f32_e32 v82, v36, v35

.LBB0_186:
	s_or_b64 exec, exec, s[44:45]
	v_lshlrev_b32_e32 v7, 6, v157
	v_mov_b32_e32 v131, v129
	v_lshlrev_b32_e32 v21, 2, v157
	v_lshlrev_b32_e32 v22, 13, v6
	v_and_b32_e32 v6, 0x3000, v7
	v_add_u32_e32 v168, 0x18000, v158
	v_lshl_add_u64 v[8:9], s[88:89], 0, v[128:129]
	v_lshl_add_u64 v[16:17], s[2:3], 0, v[128:129]
	v_lshl_add_u64 v[18:19], s[2:3], 0, v[130:131]
	v_and_b32_e32 v20, 0x3c0, v7
	v_and_b32_e32 v21, 32, v21
	v_or_b32_e32 v23, 0x10000, v6
	v_and_b32_e32 v6, 48, v157
	v_readfirstlane_b32 s3, v168
	v_add_u32_e32 v169, 0x1a000, v158
	v_lshl_add_u64 v[10:11], s[88:89], 0, v[130:131]
	v_bitop3_b32 v20, v20, v21, v6 bitop3:0x36
	v_lshl_add_u64 v[6:7], v[8:9], 0, s[72:73]
	s_mov_b32 m0, s3
	v_readfirstlane_b32 s3, v169
	v_add_u32_e32 v170, 0x8000, v158
	v_lshl_add_u64 v[12:13], s[94:95], 0, v[128:129]
	s_waitcnt vmcnt(4)
	s_barrier
	global_load_lds_dwordx4 v[6:7], off
	v_lshl_add_u64 v[6:7], v[10:11], 0, s[72:73]
	s_mov_b32 m0, s3
	v_readfirstlane_b32 s3, v170
	v_add_u32_e32 v171, 0xa000, v158
	v_lshl_add_u64 v[14:15], s[94:95], 0, v[130:131]
	global_load_lds_dwordx4 v[6:7], off
	v_lshl_add_u64 v[6:7], v[12:13], 0, s[72:73]
	s_mov_b32 m0, s3
	v_readfirstlane_b32 s3, v171
	v_add_u32_e32 v172, 0x1c000, v158
	global_load_lds_dwordx4 v[6:7], off
	v_lshl_add_u64 v[6:7], v[14:15], 0, s[72:73]
	s_mov_b32 m0, s3
	v_readfirstlane_b32 s3, v172
	v_add_u32_e32 v173, 0x1e000, v158
	global_load_lds_dwordx4 v[6:7], off
	v_lshl_add_u64 v[6:7], v[16:17], 0, s[72:73]
	s_mov_b32 m0, s3
	v_readfirstlane_b32 s3, v173
	global_load_lds_dwordx4 v[6:7], off
	v_lshl_add_u64 v[6:7], v[18:19], 0, s[72:73]
	s_mov_b32 m0, s3
	s_lshl_b64 s[94:95], s[92:93], 1
	global_load_lds_dwordx4 v[6:7], off
	s_lshr_b64 s[44:45], s[92:93], 31
	s_lshr_b32 s2, s53, 6
	s_mul_i32 s44, s44, s53
	s_mul_hi_u32 s45, s94, s53
	s_xor_b64 s[4:5], s[4:5], -1
	s_add_i32 s3, s2, -2
	s_add_i32 s45, s45, s44
	s_mul_i32 s44, s94, s53
	v_add_u32_e32 v0, v2, v0
	s_add_u32 s44, s42, s44
	v_add_u32_e32 v2, v5, v3
	v_add_lshl_u32 v0, v0, v1, 1
	v_mov_b32_e32 v1, v129
	s_addc_u32 s45, s43, s45
	v_add_lshl_u32 v2, v2, v4, 1
	v_mov_b32_e32 v3, v129
	v_lshl_add_u64 v[132:133], s[44:45], 0, v[0:1]
	v_lshl_add_u64 v[134:135], s[44:45], 0, v[2:3]
	s_mul_i32 s44, s66, s53
	s_mul_hi_u32 s45, s91, s53
	s_add_i32 s45, s45, s44
	s_mul_i32 s44, s91, s53
	s_lshl_b64 s[44:45], s[44:45], 1
	s_add_u32 s44, s34, s44
	s_addc_u32 s45, s35, s45
	v_lshl_add_u64 v[136:137], s[44:45], 0, v[0:1]
	v_lshl_add_u64 v[138:139], s[44:45], 0, v[2:3]
	s_add_u32 s44, s92, 0x80
	s_addc_u32 s45, s93, 0
	s_mul_i32 s45, s45, s53
	s_mul_hi_u32 s69, s44, s53
	s_add_i32 s45, s69, s45
	s_mul_i32 s44, s44, s53
	s_lshl_b64 s[44:45], s[44:45], 1
	s_add_u32 s42, s42, s44
	s_addc_u32 s43, s43, s45
	v_lshl_add_u64 v[140:141], s[42:43], 0, v[0:1]
	v_lshl_add_u64 v[142:143], s[42:43], 0, v[2:3]
	s_add_u32 s42, s91, 0x80
	s_addc_u32 s43, s66, 0
	s_mul_i32 s43, s43, s53
	s_mul_hi_u32 s44, s42, s53
	s_add_i32 s43, s44, s43
	s_mul_i32 s42, s42, s53
	s_lshl_b64 s[42:43], s[42:43], 1
	s_add_u32 s34, s34, s42
	s_waitcnt vmcnt(6)
	s_addc_u32 s35, s35, s43
	v_lshl_add_u64 v[144:145], s[34:35], 0, v[0:1]
	v_mov_b32_e32 v0, 0
	v_lshl_add_u64 v[146:147], s[34:35], 0, v[2:3]
	s_lshl_b32 s44, s53, 8
	s_add_u32 s76, s54, 0x80
	s_addc_u32 s77, s55, 0
	s_sub_u32 s72, s54, s44
	s_subb_u32 s73, s55, 0
	s_add_u32 s72, s72, 0x100
	s_addc_u32 s73, s73, 0
	s_add_u32 s42, s88, 0x100
	s_addc_u32 s43, s89, 0
	s_add_u32 s78, s88, s44
	s_addc_u32 s79, s89, 0
	s_add_u32 s78, s78, 0x100
	s_addc_u32 s79, s79, 0
	s_mov_b32 s34, 0
	v_readfirstlane_b32 s35, v158
	v_add_u32_e32 v174, 0xc000, v158
	v_add_u32_e32 v175, 0xe000, v158
	v_add_u32_e32 v164, v23, v20
	v_add_u32_e32 v162, v22, v20
	v_mov_b32_e32 v1, v0
	v_mov_b32_e32 v2, v0
	v_mov_b32_e32 v3, v0
	v_mov_b32_e32 v4, v0
	v_mov_b32_e32 v5, v0
	v_mov_b32_e32 v6, v0
	v_mov_b32_e32 v7, v0
	v_mov_b32_e32 v8, v0
	v_mov_b32_e32 v9, v0
	v_mov_b32_e32 v10, v0
	v_mov_b32_e32 v11, v0
	v_mov_b32_e32 v12, v0
	v_mov_b32_e32 v13, v0
	v_mov_b32_e32 v14, v0
	v_mov_b32_e32 v15, v0
	v_mov_b32_e32 v16, v0
	v_mov_b32_e32 v17, v0
	v_mov_b32_e32 v18, v0
	v_mov_b32_e32 v19, v0
	v_mov_b32_e32 v20, v0
	v_mov_b32_e32 v21, v0
	v_mov_b32_e32 v22, v0
	v_mov_b32_e32 v23, v0
	v_mov_b32_e32 v24, v0
	v_mov_b32_e32 v25, v0
	v_mov_b32_e32 v26, v0
	v_mov_b32_e32 v27, v0
	v_mov_b32_e32 v28, v0
	v_mov_b32_e32 v29, v0
	v_mov_b32_e32 v30, v0
	v_mov_b32_e32 v31, v0
	v_mov_b32_e32 v32, v0
	v_mov_b32_e32 v33, v0
	v_mov_b32_e32 v34, v0
	v_mov_b32_e32 v35, v0
	v_mov_b32_e32 v36, v0
	v_mov_b32_e32 v37, v0
	v_mov_b32_e32 v38, v0
	v_mov_b32_e32 v39, v0
	v_mov_b32_e32 v40, v0
	v_mov_b32_e32 v41, v0
	v_mov_b32_e32 v42, v0
	v_mov_b32_e32 v43, v0
	v_mov_b32_e32 v44, v0
	v_mov_b32_e32 v45, v0
	v_mov_b32_e32 v46, v0
	v_mov_b32_e32 v47, v0
	v_mov_b32_e32 v48, v0
	v_mov_b32_e32 v49, v0
	v_mov_b32_e32 v50, v0
	v_mov_b32_e32 v51, v0
	v_mov_b32_e32 v52, v0
	v_mov_b32_e32 v53, v0
	v_mov_b32_e32 v54, v0
	v_mov_b32_e32 v55, v0
	v_mov_b32_e32 v56, v0
	v_mov_b32_e32 v57, v0
	v_mov_b32_e32 v58, v0
	v_mov_b32_e32 v59, v0
	v_mov_b32_e32 v60, v0
	v_mov_b32_e32 v61, v0
	v_mov_b32_e32 v62, v0
	v_mov_b32_e32 v63, v0
	v_mov_b32_e32 v64, v0
	v_mov_b32_e32 v65, v0
	v_mov_b32_e32 v66, v0
	v_mov_b32_e32 v67, v0
	v_mov_b32_e32 v68, v0
	v_mov_b32_e32 v69, v0
	v_mov_b32_e32 v70, v0
	v_mov_b32_e32 v71, v0
	v_mov_b32_e32 v72, v0
	v_mov_b32_e32 v73, v0
	v_mov_b32_e32 v74, v0
	v_mov_b32_e32 v75, v0
	v_mov_b32_e32 v76, v0
	v_mov_b32_e32 v77, v0
	v_mov_b32_e32 v78, v0
	v_mov_b32_e32 v79, v0
	v_mov_b32_e32 v80, v0
	v_mov_b32_e32 v81, v0
	v_mov_b32_e32 v82, v0
	v_mov_b32_e32 v83, v0
	v_mov_b32_e32 v84, v0
	v_mov_b32_e32 v85, v0
	v_mov_b32_e32 v86, v0
	v_mov_b32_e32 v87, v0
	v_mov_b32_e32 v88, v0
	v_mov_b32_e32 v89, v0
	v_mov_b32_e32 v90, v0
	v_mov_b32_e32 v91, v0
	v_mov_b32_e32 v92, v0
	v_mov_b32_e32 v93, v0
	v_mov_b32_e32 v94, v0
	v_mov_b32_e32 v95, v0
	v_mov_b32_e32 v96, v0
	v_mov_b32_e32 v97, v0
	v_mov_b32_e32 v98, v0
	v_mov_b32_e32 v99, v0
	v_mov_b32_e32 v100, v0
	v_mov_b32_e32 v101, v0
	v_mov_b32_e32 v102, v0
	v_mov_b32_e32 v103, v0
	v_mov_b32_e32 v104, v0
	v_mov_b32_e32 v105, v0
	v_mov_b32_e32 v106, v0
	v_mov_b32_e32 v107, v0
	v_mov_b32_e32 v108, v0
	v_mov_b32_e32 v109, v0
	v_mov_b32_e32 v110, v0
	v_mov_b32_e32 v111, v0
	v_mov_b32_e32 v112, v0
	v_mov_b32_e32 v113, v0
	v_mov_b32_e32 v114, v0
	v_mov_b32_e32 v115, v0
	v_mov_b32_e32 v116, v0
	v_mov_b32_e32 v117, v0
	v_mov_b32_e32 v118, v0
	v_mov_b32_e32 v119, v0
	v_mov_b32_e32 v120, v0
	v_mov_b32_e32 v121, v0
	v_mov_b32_e32 v122, v0
	v_mov_b32_e32 v123, v0
	v_mov_b32_e32 v124, v0
	v_mov_b32_e32 v125, v0
	v_mov_b32_e32 v126, v0
	v_mov_b32_e32 v127, v0
	s_barrier
